# ln1_route router-weight LDS fill de-serialised: 8 coalesced global_load_dwordx4 in flight with counted vmcnt waits instead of 16 serialised dword load pairs
# speedup vs baseline: 1.0571x; 1.0045x over previous
.LBB0_563:
	s_or_b64 exec, exec, s[0:1]
	v_readlane_b32 s0, v254, 26
	v_readlane_b32 s1, v254, 27
	v_mov_b32_e32 v16, v195
	s_waitcnt lgkmcnt(0)
	v_mov_b32_e32 v0, s0
	v_mov_b32_e32 v1, s1
	s_movk_i32 s2, 0x4000
	s_barrier
	s_nop 0
	v_readfirstlane_b32 s0, v0
	v_readfirstlane_b32 s1, v1
	v_cmp_gt_i32_e32 vcc, s2, v16
	s_and_saveexec_b64 s[2:3], vcc
	v_readlane_b32 s12, v254, 43
	v_readlane_b32 s24, v254, 19
	v_readlane_b32 s25, v254, 30
	v_readlane_b32 s13, v254, 44
	v_readlane_b32 s14, v254, 45
	v_readlane_b32 s15, v254, 46
	s_cbranch_execz .LBB0_576
	v_lshlrev_b32_e32 v112, 4, v16
	v_add_u32_e32 v113, 0x2000, v112
	v_add_u32_e32 v114, 0x4000, v112
	v_add_u32_e32 v115, 0x6000, v112
	v_add_u32_e32 v116, 0x8000, v112
	v_add_u32_e32 v117, 0xa000, v112
	v_add_u32_e32 v118, 0xc000, v112
	v_add_u32_e32 v119, 0xe000, v112
	global_load_dwordx4 v[80:83], v112, s[12:13]
	global_load_dwordx4 v[84:87], v113, s[12:13]
	global_load_dwordx4 v[88:91], v114, s[12:13]
	global_load_dwordx4 v[92:95], v115, s[12:13]
	global_load_dwordx4 v[96:99], v116, s[12:13]
	global_load_dwordx4 v[100:103], v117, s[12:13]
	global_load_dwordx4 v[104:107], v118, s[12:13]
	global_load_dwordx4 v[108:111], v119, s[12:13]
	v_and_b32_e32 v120, 3, v16
	v_lshlrev_b32_e32 v120, 14, v120
	v_lshrrev_b32_e32 v121, 2, v16
	v_lshl_add_u32 v120, v121, 2, v120
	s_waitcnt vmcnt(7)
	ds_write_b32 v120, v80
	ds_write_b32 v120, v81 offset:4096
	ds_write_b32 v120, v82 offset:8192
	ds_write_b32 v120, v83 offset:12288
	s_waitcnt vmcnt(6)
	ds_write_b32 v120, v84 offset:512
	ds_write_b32 v120, v85 offset:4608
	ds_write_b32 v120, v86 offset:8704
	ds_write_b32 v120, v87 offset:12800
	s_waitcnt vmcnt(5)
	ds_write_b32 v120, v88 offset:1024
	ds_write_b32 v120, v89 offset:5120
	ds_write_b32 v120, v90 offset:9216
	ds_write_b32 v120, v91 offset:13312
	s_waitcnt vmcnt(4)
	ds_write_b32 v120, v92 offset:1536
	ds_write_b32 v120, v93 offset:5632
	ds_write_b32 v120, v94 offset:9728
	ds_write_b32 v120, v95 offset:13824
	s_waitcnt vmcnt(3)
	ds_write_b32 v120, v96 offset:2048
	ds_write_b32 v120, v97 offset:6144
	ds_write_b32 v120, v98 offset:10240
	ds_write_b32 v120, v99 offset:14336
	s_waitcnt vmcnt(2)
	ds_write_b32 v120, v100 offset:2560
	ds_write_b32 v120, v101 offset:6656
	ds_write_b32 v120, v102 offset:10752
	ds_write_b32 v120, v103 offset:14848
	s_waitcnt vmcnt(1)
	ds_write_b32 v120, v104 offset:3072
	ds_write_b32 v120, v105 offset:7168
	ds_write_b32 v120, v106 offset:11264
	ds_write_b32 v120, v107 offset:15360
	s_waitcnt vmcnt(0)
	ds_write_b32 v120, v108 offset:3584
	ds_write_b32 v120, v109 offset:7680
	ds_write_b32 v120, v110 offset:11776
	ds_write_b32 v120, v111 offset:15872
